# q up-projection epilogue: all 8 rope-table row loads issued once at epilogue start (with the row-stat loads) into registers that are dead there, per-block vmcnt(0) waits replaced by counted waits, so
# speedup vs baseline: 1.0340x; 1.0051x over previous
; __device__ __forceinline__ unsigned cvt_pk_bf16(float lo, float hi) { unsigned r; asm volatile("v_cvt_pk_bf16_f32 %0, %1, %2" : "=v"(r) : "v"(lo), "v"(hi)); return r; }
; __device__ __forceinline__ float ssq_val(ssq_t v) { return (float)v * SSQ_IFX; }
;     __device__ __forceinline__ void operator()(const f32x4 (&acc)[2][2][4][2], const Unit& u, int wr, int wc, int fr, int fq) const {
;         const int row0 = u.pm * BM + wr * 64 + fr;
;         ssq_t sv[8]; float rsv[8];
; #pragma unroll
;         for (int i = 0; i < 8; ++i) sv[i] = ssq[row0 + (i >> 2) * HALF + (i & 3) * 16];
; #pragma unroll
;         for (int i = 0; i < 8; ++i) rsv[i] = QS_B / sqrtf(ssq_val(sv[i]) * (1.0f / 384.0f) + EPS);
; #pragma unroll
;         for (int ai = 0; ai < 2; ++ai)
; #pragma unroll
;             for (int m = 0; m < 4; ++m) {
;                 const int row = row0 + ai * HALF + m * 16;
;                 const float rs = rsv[ai * 4 + m];
; #pragma unroll
;                 for (int bj = 0; bj < 2; ++bj) {
;                     const int colw = u.pn * BM + bj * HALF + wc * 32, col0 = colw + 8 * fq;
;                     const bool rope = (colw % 96) == 64 && colw < 576;
;                     f32x4 v0 = acc[ai][bj][m][0] * rs, v1 = acc[ai][bj][m][1] * rs;
;                     if (rope) {
;                         const float* tp = ropB + ((size_t)row * 16 + ((col0 - colw) >> 1)) * 2;
;                         const f32x4 c0 = *(const f32x4*)tp, c1 = *(const f32x4*)(tp + 4);
;                         f32x4 w0, w1;
;                         w0[0] = v0[0] * c0[0] - v0[1] * c0[1]; w0[1] = v0[1] * c0[0] + v0[0] * c0[1];
;                         w0[2] = v0[2] * c0[2] - v0[3] * c0[3]; w0[3] = v0[3] * c0[2] + v0[2] * c0[3];
;                         w1[0] = v1[0] * c1[0] - v1[1] * c1[1]; w1[1] = v1[1] * c1[0] + v1[0] * c1[1];
;                         w1[2] = v1[2] * c1[2] - v1[3] * c1[3]; w1[3] = v1[3] * c1[2] + v1[2] * c1[3];
;                         v0 = w0; v1 = w1;
;                     }
;                     u32x4 w; w.x = cvt_pk_bf16(v0[0], v0[1]); w.y = cvt_pk_bf16(v0[2], v0[3]); w.z = cvt_pk_bf16(v1[0], v1[1]); w.w = cvt_pk_bf16(v1[2], v1[3]);
;                     *(u32x4*)(O + (size_t)row * QMP + col0) = w;
.LBB0_713:
	s_lshl_b32 s2, s31, 8
	s_add_i32 s2, s2, s4
	v_mbcnt_lo_u32_b32 v0, -1, 0
	v_mbcnt_hi_u32_b32 v0, -1, v0
	s_nop 0
	v_and_or_b32 v140, v0, 15, s2
	v_ashrrev_i32_e32 v141, 31, v140
	v_lshl_add_u64 v[142:143], v[140:141], 3, s[18:19]
	global_load_dwordx2 v[156:157], v[142:143], off
	global_load_dwordx2 v[154:155], v[142:143], off offset:128
	global_load_dwordx2 v[152:153], v[142:143], off offset:256
	global_load_dwordx2 v[150:151], v[142:143], off offset:384
	global_load_dwordx2 v[148:149], v[142:143], off offset:1024
	global_load_dwordx2 v[146:147], v[142:143], off offset:1152
	global_load_dwordx2 v[144:145], v[142:143], off offset:1280
	s_nop 0
	global_load_dwordx2 v[142:143], v[142:143], off offset:1408
	s_lshl_b32 s86, s30, 8
	s_or_b32 s86, s86, s5
	s_mul_hi_i32 s87, s86, 0x2aaaaaab
	s_lshr_b32 s88, s87, 31
	s_lshr_b32 s87, s87, 4
	s_add_i32 s87, s87, s88
	s_mulk_i32 s87, 0x60
	s_sub_i32 s87, s86, s87
	s_cmp_eq_u32 s87, 64
	s_cselect_b32 s88, 0x240, 0
	s_cmp_eq_u32 s87, 32
	s_cselect_b32 s88, 0x1c0, s88
	s_cmp_lt_i32 s86, s88
	s_cbranch_scc0 .Lp3a_pf_skip
	v_mbcnt_lo_u32_b32 v250, -1, 0
	v_mbcnt_hi_u32_b32 v250, -1, v250
	v_and_b32_e32 v250, 48, v250
	v_lshlrev_b32_e32 v250, 1, v250
	v_lshlrev_b64 v[248:249], 7, v[140:141]
	v_mov_b32_e32 v251, 0
	v_lshl_add_u64 v[248:249], v[248:249], 0, v[250:251]
	v_lshl_add_u64 v[248:249], s[20:21], 0, v[248:249]
	s_mov_b64 s[88:89], 0x1000
	s_mov_b64 s[90:91], 0x4000
	s_mov_b64 s[92:93], 0x5000
	global_load_dwordx4 v[178:181], v[248:249], off
	global_load_dwordx4 v[182:185], v[248:249], off offset:16
	global_load_dwordx4 v[186:189], v[248:249], off offset:2048
	global_load_dwordx4 v[190:193], v[248:249], off offset:2064
	v_lshl_add_u64 v[250:251], v[248:249], 0, s[88:89]
	global_load_dwordx4 v[194:197], v[250:251], off
	global_load_dwordx4 v[198:201], v[250:251], off offset:16
	global_load_dwordx4 v[202:205], v[250:251], off offset:2048
	global_load_dwordx4 v[206:209], v[250:251], off offset:2064
	v_lshl_add_u64 v[250:251], v[248:249], 0, s[90:91]
	global_load_dwordx4 v[210:213], v[250:251], off
	global_load_dwordx4 v[214:217], v[250:251], off offset:16
	global_load_dwordx4 v[218:221], v[250:251], off offset:2048
	global_load_dwordx4 v[228:231], v[250:251], off offset:2064
	v_lshl_add_u64 v[250:251], v[248:249], 0, s[92:93]
	global_load_dwordx4 v[232:235], v[250:251], off
	global_load_dwordx4 v[236:239], v[250:251], off offset:16
	global_load_dwordx4 v[240:243], v[250:251], off offset:2048
	global_load_dwordx4 v[244:247], v[250:251], off offset:2064
.Lp3a_pf_skip:
	v_lshrrev_b32_e32 v0, 1, v0
	v_and_b32_e32 v0, 24, v0
	v_lshlrev_b64 v[166:167], 7, v[140:141]
	s_waitcnt vmcnt(0) lgkmcnt(0)
	v_ffbh_u32_e32 v158, v157
	v_min_u32_e32 v158, 32, v158
	v_lshlrev_b64 v[156:157], v158, v[156:157]
	v_min_u32_e32 v156, 1, v156
	v_or_b32_e32 v156, v157, v156
	v_cvt_f32_u32_e32 v156, v156
	v_sub_u32_e32 v157, 32, v158
	v_ldexp_f32 v156, v156, v157
	v_mul_f32_e32 v156, 0x33800000, v156
	v_fmamk_f32 v156, v156, 0x3b2aaaab, v226
	s_lshl_b32 s2, s30, 8
	s_or_b32 s30, s2, s5
	s_mul_hi_i32 s2, s30, 0x2aaaaaab
	s_lshr_b32 s3, s2, 31
	s_lshr_b32 s2, s2, 4
	s_add_i32 s2, s2, s3
	s_mulk_i32 s2, 0x60
	s_sub_i32 s2, s30, s2
	s_cmp_eq_u32 s2, 64
	s_cselect_b64 s[2:3], -1, 0
	s_cmpk_lt_i32 s30, 0x240
	s_cselect_b64 s[8:9], -1, 0
	v_rsq_f32_e32 v156, v156
	s_nop 0
	v_mul_f32_e32 v156, s69, v156
	s_and_b64 s[2:3], s[8:9], s[2:3]
	v_pk_mul_f32 v[158:159], v[126:127], v[156:157] op_sel_hi:[1,0]
	v_cndmask_b32_e64 v126, 0, 1, s[2:3]
	v_pk_mul_f32 v[162:163], v[128:129], v[156:157] op_sel_hi:[1,0]
	v_pk_mul_f32 v[160:161], v[132:133], v[156:157] op_sel_hi:[1,0]
	v_pk_mul_f32 v[130:131], v[130:131], v[156:157] op_sel_hi:[1,0]
	v_cmp_ne_u32_e64 s[8:9], 1, v126
	s_andn2_b64 vcc, exec, s[2:3]
	v_lshl_add_u64 v[132:133], s[20:21], 0, v[166:167]
	v_lshlrev_b32_e32 v126, 2, v0
	s_cbranch_vccnz .LBB0_715
	v_mov_b32_e32 v127, v1
	v_lshl_add_u64 v[128:129], v[132:133], 0, v[126:127]
	s_waitcnt vmcnt(14) lgkmcnt(0)
	v_mov_b64_e32 v[166:167], v[178:179]
	v_mov_b64_e32 v[168:169], v[180:181]
	v_mov_b64_e32 v[170:171], v[182:183]
	v_mov_b64_e32 v[172:173], v[184:185]
	v_pk_mul_f32 v[174:175], v[158:159], v[166:167] op_sel:[1,1] op_sel_hi:[0,1]
	v_pk_mul_f32 v[128:129], v[158:159], v[166:167]
	v_pk_fma_f32 v[158:159], v[158:159], v[166:167], v[174:175] op_sel_hi:[1,0,1]
	v_pk_mul_f32 v[176:177], v[130:131], v[170:171] op_sel:[1,1] op_sel_hi:[0,1]
	v_mul_f32_e32 v158, v163, v169
	v_pk_fma_f32 v[166:167], v[162:163], v[168:169], v[158:159] op_sel_hi:[1,1,0] neg_lo:[0,0,1] neg_hi:[0,0,1]
	v_mul_f32_e32 v158, v162, v169
	v_pk_fma_f32 v[168:169], v[162:163], v[168:169], v[158:159] op_sel:[1,0,0] op_sel_hi:[0,1,0]
	v_pk_mul_f32 v[162:163], v[130:131], v[170:171]
	v_pk_fma_f32 v[130:131], v[130:131], v[170:171], v[176:177] op_sel_hi:[1,0,1]
	v_sub_f32_e32 v158, v128, v174
	v_mul_f32_e32 v130, v161, v173
	v_pk_fma_f32 v[170:171], v[160:161], v[172:173], v[130:131] op_sel_hi:[1,1,0] neg_lo:[0,0,1] neg_hi:[0,0,1]
	v_mul_f32_e32 v130, v160, v173
	v_pk_fma_f32 v[172:173], v[160:161], v[172:173], v[130:131] op_sel:[1,0,0] op_sel_hi:[0,1,0]
	v_sub_f32_e32 v130, v162, v176
	v_mov_b32_e32 v162, v166
	v_mov_b32_e32 v163, v168
	v_mov_b32_e32 v160, v170
	v_mov_b32_e32 v161, v172
; __device__ __forceinline__ unsigned cvt_pk_bf16(float lo, float hi) { unsigned r; asm volatile("v_cvt_pk_bf16_f32 %0, %1, %2" : "=v"(r) : "v"(lo), "v"(hi)); return r; }
;     __device__ __forceinline__ void operator()(const f32x4 (&acc)[2][2][4][2], const Unit& u, int wr, int wc, int fr, int fq) const {
;     ...
;             for (int m = 0; m < 4; ++m) {
;                 const int row = row0 + ai * HALF + m * 16;
;                 const float rs = rsv[ai * 4 + m];
; #pragma unroll
;                 for (int bj = 0; bj < 2; ++bj) {
;                     const int colw = u.pn * BM + bj * HALF + wc * 32, col0 = colw + 8 * fq;
;                     const bool rope = (colw % 96) == 64 && colw < 576;
;                     f32x4 v0 = acc[ai][bj][m][0] * rs, v1 = acc[ai][bj][m][1] * rs;
;                     if (rope) {
;                         const float* tp = ropB + ((size_t)row * 16 + ((col0 - colw) >> 1)) * 2;
;                         const f32x4 c0 = *(const f32x4*)tp, c1 = *(const f32x4*)(tp + 4);
;                         f32x4 w0, w1;
;                         w0[0] = v0[0] * c0[0] - v0[1] * c0[1]; w0[1] = v0[1] * c0[0] + v0[0] * c0[1];
;                         w0[2] = v0[2] * c0[2] - v0[3] * c0[3]; w0[3] = v0[3] * c0[2] + v0[2] * c0[3];
;                         w1[0] = v1[0] * c1[0] - v1[1] * c1[1]; w1[1] = v1[1] * c1[0] + v1[0] * c1[1];
;                         w1[2] = v1[2] * c1[2] - v1[3] * c1[3]; w1[3] = v1[3] * c1[2] + v1[2] * c1[3];
;                         v0 = w0; v1 = w1;
;                     }
;                     u32x4 w; w.x = cvt_pk_bf16(v0[0], v0[1]); w.y = cvt_pk_bf16(v0[2], v0[3]); w.z = cvt_pk_bf16(v1[0], v1[1]); w.w = cvt_pk_bf16(v1[2], v1[3]);
;                     *(u32x4*)(O + (size_t)row * QMP + col0) = w;
.LBB0_715:
	v_cvt_pk_bf16_f32 v166, v158, v159
	v_cvt_pk_bf16_f32 v167, v162, v163
	v_cvt_pk_bf16_f32 v168, v130, v131
	v_mov_b64_e32 v[130:131], s[16:17]
	v_mad_i64_i32 v[130:131], s[2:3], v140, s75, v[130:131]
	s_or_b32 s10, s30, 0x80
	s_mul_hi_i32 s2, s10, 0x2aaaaaab
	s_lshr_b32 s3, s2, 31
	s_lshr_b32 s2, s2, 4
	s_add_i32 s2, s2, s3
	s_mulk_i32 s2, 0x60
	s_sub_i32 s2, s10, s2
	s_cmp_eq_u32 s2, 64
	v_or_b32_e32 v128, s30, v0
	s_cselect_b64 s[2:3], -1, 0
	s_cmpk_lt_i32 s10, 0x240
	v_ashrrev_i32_e32 v129, 31, v128
	s_cselect_b64 s[10:11], -1, 0
	v_cvt_pk_bf16_f32 v169, v160, v161
	v_lshl_add_u64 v[158:159], v[128:129], 1, v[130:131]
	v_mov_b32_e32 v160, v156
	v_mov_b32_e32 v161, v156
	s_and_b64 s[2:3], s[10:11], s[2:3]
	v_mov_b32_e32 v157, v156
	global_store_dwordx4 v[158:159], v[166:169], off nt
	v_pk_mul_f32 v[158:159], v[124:125], v[160:161]
	v_pk_mul_f32 v[124:125], v[120:121], v[160:161]
	v_cndmask_b32_e64 v120, 0, 1, s[2:3]
	v_pk_mul_f32 v[122:123], v[122:123], v[156:157]
	v_cmp_ne_u32_e64 s[10:11], 1, v120
	s_andn2_b64 vcc, exec, s[2:3]
	v_pk_mul_f32 v[118:119], v[118:119], v[156:157]
	s_cbranch_vccnz .LBB0_717
	v_mov_b32_e32 v127, v1
	v_lshl_add_u64 v[120:121], v[132:133], 0, v[126:127]
	s_waitcnt vmcnt(15) lgkmcnt(0)
	v_mov_b64_e32 v[160:161], v[178:179]
	v_mov_b64_e32 v[162:163], v[180:181]
	v_mov_b64_e32 v[166:167], v[182:183]
	v_mov_b64_e32 v[168:169], v[184:185]
	v_pk_mul_f32 v[132:133], v[122:123], v[160:161] op_sel:[1,1] op_sel_hi:[0,1]
	v_pk_mul_f32 v[120:121], v[122:123], v[160:161]
	v_pk_fma_f32 v[122:123], v[122:123], v[160:161], v[132:133] op_sel_hi:[1,0,1]
	s_nop 0
	v_mul_f32_e32 v122, v159, v163
	v_pk_fma_f32 v[156:157], v[158:159], v[162:163], v[122:123] op_sel_hi:[1,1,0] neg_lo:[0,0,1] neg_hi:[0,0,1]
	v_mul_f32_e32 v122, v158, v163
	v_pk_fma_f32 v[160:161], v[158:159], v[162:163], v[122:123] op_sel:[1,0,0] op_sel_hi:[0,1,0]
	v_pk_mul_f32 v[162:163], v[118:119], v[166:167] op_sel:[1,1] op_sel_hi:[0,1]
	v_pk_mul_f32 v[158:159], v[118:119], v[166:167]
	v_pk_fma_f32 v[118:119], v[118:119], v[166:167], v[162:163] op_sel_hi:[1,0,1]
	v_sub_f32_e32 v122, v120, v132
	v_mul_f32_e32 v118, v125, v169
	v_pk_fma_f32 v[166:167], v[124:125], v[168:169], v[118:119] op_sel_hi:[1,1,0] neg_lo:[0,0,1] neg_hi:[0,0,1]
	v_mul_f32_e32 v118, v124, v169
	v_pk_fma_f32 v[168:169], v[124:125], v[168:169], v[118:119] op_sel:[1,0,0] op_sel_hi:[0,1,0]
	v_sub_f32_e32 v118, v158, v162
	v_mov_b32_e32 v158, v156
	v_mov_b32_e32 v159, v160
	v_mov_b32_e32 v124, v166
	v_mov_b32_e32 v125, v168
.LBB0_717:
	v_ffbh_u32_e32 v120, v155
	v_min_u32_e32 v127, 32, v120
	v_lshlrev_b64 v[120:121], v127, v[154:155]
	v_min_u32_e32 v120, 1, v120
	v_or_b32_e32 v120, v121, v120
	v_cvt_f32_u32_e32 v120, v120
	v_sub_u32_e32 v121, 32, v127
	s_ashr_i32 s31, s30, 31
	v_cvt_pk_bf16_f32 v154, v122, v123
	v_ldexp_f32 v120, v120, v121
	v_mul_f32_e32 v120, 0x33800000, v120
	v_fmamk_f32 v120, v120, 0x3b2aaaab, v226
	v_cvt_pk_bf16_f32 v155, v158, v159
	v_cvt_pk_bf16_f32 v156, v118, v119
	v_lshl_add_u64 v[118:119], v[0:1], 0, s[30:31]
	v_lshl_add_u64 v[122:123], v[118:119], 1, v[130:131]
	v_cvt_pk_bf16_f32 v157, v124, v125
	global_store_dwordx4 v[122:123], v[154:157], off offset:256 nt
	v_or_b32_e32 v122, 16, v140
	v_ashrrev_i32_e32 v123, 31, v122
	v_lshlrev_b64 v[130:131], 7, v[122:123]
	v_rsq_f32_e32 v120, v120
	s_nop 0
	v_mul_f32_e32 v120, s69, v120
	v_pk_mul_f32 v[124:125], v[116:117], v[120:121] op_sel_hi:[1,0]
	v_pk_mul_f32 v[114:115], v[114:115], v[120:121] op_sel_hi:[1,0]
	v_pk_mul_f32 v[116:117], v[112:113], v[120:121] op_sel_hi:[1,0]
	v_pk_mul_f32 v[110:111], v[110:111], v[120:121] op_sel_hi:[1,0]
	s_and_b64 vcc, exec, s[8:9]
	v_lshl_add_u64 v[112:113], s[20:21], 0, v[130:131]
	s_cbranch_vccnz .LBB0_719
	v_mov_b32_e32 v127, v1
	v_lshl_add_u64 v[154:155], v[112:113], 0, v[126:127]
	s_waitcnt vmcnt(14) lgkmcnt(0)
	v_mov_b64_e32 v[130:131], v[186:187]
	v_mov_b64_e32 v[132:133], v[188:189]
	v_mov_b64_e32 v[154:155], v[190:191]
	v_mov_b64_e32 v[156:157], v[192:193]
	v_pk_mul_f32 v[160:161], v[114:115], v[130:131] op_sel:[1,1] op_sel_hi:[0,1]
	v_mul_f32_e32 v0, v125, v133
	v_pk_mul_f32 v[158:159], v[114:115], v[130:131]
	v_pk_fma_f32 v[114:115], v[114:115], v[130:131], v[160:161] op_sel_hi:[1,0,1]
	v_pk_fma_f32 v[130:131], v[124:125], v[132:133], v[0:1] op_sel_hi:[1,1,0] neg_lo:[0,0,1] neg_hi:[0,0,1]
	v_mul_f32_e32 v0, v124, v133
	v_pk_fma_f32 v[132:133], v[124:125], v[132:133], v[0:1] op_sel:[1,0,0] op_sel_hi:[0,1,0]
	v_pk_mul_f32 v[162:163], v[110:111], v[154:155] op_sel:[1,1] op_sel_hi:[0,1]
	v_mul_f32_e32 v0, v117, v157
	v_pk_mul_f32 v[124:125], v[110:111], v[154:155]
	v_pk_fma_f32 v[110:111], v[110:111], v[154:155], v[162:163] op_sel_hi:[1,0,1]
	v_pk_fma_f32 v[154:155], v[116:117], v[156:157], v[0:1] op_sel_hi:[1,1,0] neg_lo:[0,0,1] neg_hi:[0,0,1]
	v_mul_f32_e32 v0, v116, v157
	v_pk_fma_f32 v[156:157], v[116:117], v[156:157], v[0:1] op_sel:[1,0,0] op_sel_hi:[0,1,0]
	v_sub_f32_e32 v114, v158, v160
	v_sub_f32_e32 v110, v124, v162
	v_mov_b32_e32 v124, v130
	v_mov_b32_e32 v125, v132
	v_mov_b32_e32 v116, v154
	v_mov_b32_e32 v117, v156
; __device__ __forceinline__ unsigned cvt_pk_bf16(float lo, float hi) { unsigned r; asm volatile("v_cvt_pk_bf16_f32 %0, %1, %2" : "=v"(r) : "v"(lo), "v"(hi)); return r; }
;     __device__ __forceinline__ void operator()(const f32x4 (&acc)[2][2][4][2], const Unit& u, int wr, int wc, int fr, int fq) const {
;     ...
;             for (int m = 0; m < 4; ++m) {
;                 const int row = row0 + ai * HALF + m * 16;
;                 const float rs = rsv[ai * 4 + m];
; #pragma unroll
;                 for (int bj = 0; bj < 2; ++bj) {
;                     const int colw = u.pn * BM + bj * HALF + wc * 32, col0 = colw + 8 * fq;
;                     const bool rope = (colw % 96) == 64 && colw < 576;
;                     f32x4 v0 = acc[ai][bj][m][0] * rs, v1 = acc[ai][bj][m][1] * rs;
;                     if (rope) {
;                         const float* tp = ropB + ((size_t)row * 16 + ((col0 - colw) >> 1)) * 2;
;                         const f32x4 c0 = *(const f32x4*)tp, c1 = *(const f32x4*)(tp + 4);
;                         f32x4 w0, w1;
;                         w0[0] = v0[0] * c0[0] - v0[1] * c0[1]; w0[1] = v0[1] * c0[0] + v0[0] * c0[1];
;                         w0[2] = v0[2] * c0[2] - v0[3] * c0[3]; w0[3] = v0[3] * c0[2] + v0[2] * c0[3];
;                         w1[0] = v1[0] * c1[0] - v1[1] * c1[1]; w1[1] = v1[1] * c1[0] + v1[0] * c1[1];
;                         w1[2] = v1[2] * c1[2] - v1[3] * c1[3]; w1[3] = v1[3] * c1[2] + v1[2] * c1[3];
;                         v0 = w0; v1 = w1;
;                     }
;                     u32x4 w; w.x = cvt_pk_bf16(v0[0], v0[1]); w.y = cvt_pk_bf16(v0[2], v0[3]); w.z = cvt_pk_bf16(v1[0], v1[1]); w.w = cvt_pk_bf16(v1[2], v1[3]);
;                     *(u32x4*)(O + (size_t)row * QMP + col0) = w;
.LBB0_719:
	v_cvt_pk_bf16_f32 v130, v114, v115
	v_cvt_pk_bf16_f32 v131, v124, v125
	v_cvt_pk_bf16_f32 v132, v110, v111
	v_mov_b64_e32 v[110:111], s[16:17]
	v_mad_i64_i32 v[110:111], s[2:3], v122, s75, v[110:111]
	v_mov_b32_e32 v121, v120
	v_cvt_pk_bf16_f32 v133, v116, v117
	v_lshl_add_u64 v[114:115], v[128:129], 1, v[110:111]
	v_mov_b32_e32 v116, v120
	v_mov_b32_e32 v117, v120
	global_store_dwordx4 v[114:115], v[130:133], off nt
	v_pk_mul_f32 v[114:115], v[108:109], v[116:117]
	v_pk_mul_f32 v[106:107], v[106:107], v[120:121]
	v_pk_mul_f32 v[108:109], v[104:105], v[116:117]
	s_and_b64 vcc, exec, s[10:11]
	v_pk_mul_f32 v[102:103], v[102:103], v[120:121]
	s_cbranch_vccnz .LBB0_721
	v_mov_b32_e32 v127, v1
	v_lshl_add_u64 v[104:105], v[112:113], 0, v[126:127]
	s_waitcnt vmcnt(15) lgkmcnt(0)
	v_mov_b64_e32 v[120:121], v[186:187]
	v_mov_b64_e32 v[122:123], v[188:189]
	v_mov_b64_e32 v[130:131], v[190:191]
	v_mov_b64_e32 v[132:133], v[192:193]
	v_mul_f32_e32 v0, v115, v123
	v_pk_mul_f32 v[112:113], v[106:107], v[120:121] op_sel:[1,1] op_sel_hi:[0,1]
	v_pk_fma_f32 v[116:117], v[114:115], v[122:123], v[0:1] op_sel_hi:[1,1,0] neg_lo:[0,0,1] neg_hi:[0,0,1]
	v_mul_f32_e32 v0, v114, v123
	v_pk_mul_f32 v[104:105], v[106:107], v[120:121]
	v_pk_fma_f32 v[106:107], v[106:107], v[120:121], v[112:113] op_sel_hi:[1,0,1]
	v_pk_fma_f32 v[120:121], v[114:115], v[122:123], v[0:1] op_sel:[1,0,0] op_sel_hi:[0,1,0]
	v_mul_f32_e32 v0, v109, v133
	v_pk_mul_f32 v[122:123], v[102:103], v[130:131] op_sel:[1,1] op_sel_hi:[0,1]
	v_pk_fma_f32 v[124:125], v[108:109], v[132:133], v[0:1] op_sel_hi:[1,1,0] neg_lo:[0,0,1] neg_hi:[0,0,1]
	v_mul_f32_e32 v0, v108, v133
	v_pk_mul_f32 v[114:115], v[102:103], v[130:131]
	v_pk_fma_f32 v[102:103], v[102:103], v[130:131], v[122:123] op_sel_hi:[1,0,1]
	v_pk_fma_f32 v[130:131], v[108:109], v[132:133], v[0:1] op_sel:[1,0,0] op_sel_hi:[0,1,0]
	v_sub_f32_e32 v106, v104, v112
	v_sub_f32_e32 v102, v114, v122
	v_mov_b32_e32 v114, v116
	v_mov_b32_e32 v115, v120
	v_mov_b32_e32 v108, v124
	v_mov_b32_e32 v109, v130
.LBB0_721:
	v_ffbh_u32_e32 v0, v153
	v_min_u32_e32 v0, 32, v0
	v_lshlrev_b64 v[104:105], v0, v[152:153]
	v_min_u32_e32 v104, 1, v104
	v_or_b32_e32 v104, v105, v104
	v_cvt_f32_u32_e32 v104, v104
	v_sub_u32_e32 v0, 32, v0
	v_ldexp_f32 v0, v104, v0
	v_mul_f32_e32 v0, 0x33800000, v0
	v_fmamk_f32 v0, v0, 0x3b2aaaab, v226
	v_cvt_pk_bf16_f32 v112, v106, v107
	v_cvt_pk_bf16_f32 v113, v114, v115
	v_cvt_pk_bf16_f32 v114, v102, v103
	v_lshl_add_u64 v[102:103], v[118:119], 1, v[110:111]
	v_cvt_pk_bf16_f32 v115, v108, v109
	global_store_dwordx4 v[102:103], v[112:115], off offset:256 nt
	v_or_b32_e32 v102, 32, v140
	v_ashrrev_i32_e32 v103, 31, v102
	v_rsq_f32_e32 v104, v0
	s_nop 0
	v_mul_f32_e32 v104, s69, v104
	v_lshlrev_b64 v[108:109], 7, v[102:103]
	v_pk_mul_f32 v[106:107], v[100:101], v[104:105] op_sel_hi:[1,0]
	v_pk_mul_f32 v[98:99], v[98:99], v[104:105] op_sel_hi:[1,0]
	v_pk_mul_f32 v[100:101], v[96:97], v[104:105] op_sel_hi:[1,0]
	v_pk_mul_f32 v[94:95], v[94:95], v[104:105] op_sel_hi:[1,0]
	s_and_b64 vcc, exec, s[8:9]
	v_lshl_add_u64 v[96:97], s[20:21], 0, v[108:109]
	s_cbranch_vccnz .LBB0_723
	v_mov_b32_e32 v127, v1
	v_lshl_add_u64 v[112:113], v[96:97], 0, v[126:127]
	s_waitcnt vmcnt(14) lgkmcnt(0)
	v_mov_b64_e32 v[108:109], v[194:195]
	v_mov_b64_e32 v[110:111], v[196:197]
	v_mov_b64_e32 v[112:113], v[198:199]
	v_mov_b64_e32 v[114:115], v[200:201]
	v_pk_mul_f32 v[120:121], v[98:99], v[108:109] op_sel:[1,1] op_sel_hi:[0,1]
	v_mul_f32_e32 v0, v107, v111
	v_pk_mul_f32 v[116:117], v[98:99], v[108:109]
	v_pk_fma_f32 v[98:99], v[98:99], v[108:109], v[120:121] op_sel_hi:[1,0,1]
	v_pk_fma_f32 v[108:109], v[106:107], v[110:111], v[0:1] op_sel_hi:[1,1,0] neg_lo:[0,0,1] neg_hi:[0,0,1]
	v_mul_f32_e32 v0, v106, v111
	v_pk_fma_f32 v[110:111], v[106:107], v[110:111], v[0:1] op_sel:[1,0,0] op_sel_hi:[0,1,0]
	v_pk_mul_f32 v[122:123], v[94:95], v[112:113] op_sel:[1,1] op_sel_hi:[0,1]
	v_mul_f32_e32 v0, v101, v115
	v_pk_mul_f32 v[106:107], v[94:95], v[112:113]
	v_pk_fma_f32 v[94:95], v[94:95], v[112:113], v[122:123] op_sel_hi:[1,0,1]
	v_pk_fma_f32 v[112:113], v[100:101], v[114:115], v[0:1] op_sel_hi:[1,1,0] neg_lo:[0,0,1] neg_hi:[0,0,1]
	v_mul_f32_e32 v0, v100, v115
	v_pk_fma_f32 v[114:115], v[100:101], v[114:115], v[0:1] op_sel:[1,0,0] op_sel_hi:[0,1,0]
	v_sub_f32_e32 v98, v116, v120
	v_sub_f32_e32 v94, v106, v122
	v_mov_b32_e32 v106, v108
	v_mov_b32_e32 v107, v110
	v_mov_b32_e32 v100, v112
	v_mov_b32_e32 v101, v114
.LBB0_723:
	v_cvt_pk_bf16_f32 v108, v98, v99
	v_cvt_pk_bf16_f32 v109, v106, v107
	v_cvt_pk_bf16_f32 v110, v94, v95
	v_mov_b64_e32 v[94:95], s[16:17]
	v_mad_i64_i32 v[94:95], s[2:3], v102, s75, v[94:95]
	v_mov_b32_e32 v105, v104
	v_cvt_pk_bf16_f32 v111, v100, v101
	v_lshl_add_u64 v[98:99], v[128:129], 1, v[94:95]
	v_mov_b32_e32 v100, v104
	v_mov_b32_e32 v101, v104
	global_store_dwordx4 v[98:99], v[108:111], off nt
	v_pk_mul_f32 v[98:99], v[92:93], v[100:101]
	v_pk_mul_f32 v[90:91], v[90:91], v[104:105]
	v_pk_mul_f32 v[92:93], v[88:89], v[100:101]
	s_and_b64 vcc, exec, s[10:11]
	v_pk_mul_f32 v[86:87], v[86:87], v[104:105]
	s_cbranch_vccnz .LBB0_725
	v_mov_b32_e32 v127, v1
	v_lshl_add_u64 v[88:89], v[96:97], 0, v[126:127]
	s_waitcnt vmcnt(15) lgkmcnt(0)
	v_mov_b64_e32 v[100:101], v[194:195]
	v_mov_b64_e32 v[102:103], v[196:197]
	v_mov_b64_e32 v[104:105], v[198:199]
	v_mov_b64_e32 v[106:107], v[200:201]
	v_pk_mul_f32 v[96:97], v[90:91], v[100:101] op_sel:[1,1] op_sel_hi:[0,1]
	v_mul_f32_e32 v0, v99, v103
	v_pk_mul_f32 v[88:89], v[90:91], v[100:101]
	v_pk_fma_f32 v[90:91], v[90:91], v[100:101], v[96:97] op_sel_hi:[1,0,1]
	v_pk_fma_f32 v[100:101], v[98:99], v[102:103], v[0:1] op_sel_hi:[1,1,0] neg_lo:[0,0,1] neg_hi:[0,0,1]
	v_mul_f32_e32 v0, v98, v103
	v_pk_fma_f32 v[102:103], v[98:99], v[102:103], v[0:1] op_sel:[1,0,0] op_sel_hi:[0,1,0]
	v_pk_mul_f32 v[108:109], v[86:87], v[104:105] op_sel:[1,1] op_sel_hi:[0,1]
	v_mul_f32_e32 v0, v93, v107
	v_pk_mul_f32 v[98:99], v[86:87], v[104:105]
	v_pk_fma_f32 v[86:87], v[86:87], v[104:105], v[108:109] op_sel_hi:[1,0,1]
	v_pk_fma_f32 v[104:105], v[92:93], v[106:107], v[0:1] op_sel_hi:[1,1,0] neg_lo:[0,0,1] neg_hi:[0,0,1]
	v_mul_f32_e32 v0, v92, v107
	v_pk_fma_f32 v[106:107], v[92:93], v[106:107], v[0:1] op_sel:[1,0,0] op_sel_hi:[0,1,0]
	v_sub_f32_e32 v90, v88, v96
	v_sub_f32_e32 v86, v98, v108
	v_mov_b32_e32 v98, v100
	v_mov_b32_e32 v99, v102
	v_mov_b32_e32 v92, v104
	v_mov_b32_e32 v93, v106
; __device__ __forceinline__ unsigned cvt_pk_bf16(float lo, float hi) { unsigned r; asm volatile("v_cvt_pk_bf16_f32 %0, %1, %2" : "=v"(r) : "v"(lo), "v"(hi)); return r; }
;     __device__ __forceinline__ void operator()(const f32x4 (&acc)[2][2][4][2], const Unit& u, int wr, int wc, int fr, int fq) const {
;     ...
;             for (int m = 0; m < 4; ++m) {
;                 const int row = row0 + ai * HALF + m * 16;
;                 const float rs = rsv[ai * 4 + m];
; #pragma unroll
;                 for (int bj = 0; bj < 2; ++bj) {
;                     const int colw = u.pn * BM + bj * HALF + wc * 32, col0 = colw + 8 * fq;
;                     const bool rope = (colw % 96) == 64 && colw < 576;
;                     f32x4 v0 = acc[ai][bj][m][0] * rs, v1 = acc[ai][bj][m][1] * rs;
;                     if (rope) {
;                         const float* tp = ropB + ((size_t)row * 16 + ((col0 - colw) >> 1)) * 2;
;                         const f32x4 c0 = *(const f32x4*)tp, c1 = *(const f32x4*)(tp + 4);
;                         f32x4 w0, w1;
;                         w0[0] = v0[0] * c0[0] - v0[1] * c0[1]; w0[1] = v0[1] * c0[0] + v0[0] * c0[1];
;                         w0[2] = v0[2] * c0[2] - v0[3] * c0[3]; w0[3] = v0[3] * c0[2] + v0[2] * c0[3];
;                         w1[0] = v1[0] * c1[0] - v1[1] * c1[1]; w1[1] = v1[1] * c1[0] + v1[0] * c1[1];
;                         w1[2] = v1[2] * c1[2] - v1[3] * c1[3]; w1[3] = v1[3] * c1[2] + v1[2] * c1[3];
;                         v0 = w0; v1 = w1;
;                     }
;                     u32x4 w; w.x = cvt_pk_bf16(v0[0], v0[1]); w.y = cvt_pk_bf16(v0[2], v0[3]); w.z = cvt_pk_bf16(v1[0], v1[1]); w.w = cvt_pk_bf16(v1[2], v1[3]);
;                     *(u32x4*)(O + (size_t)row * QMP + col0) = w;
.LBB0_725:
	v_ffbh_u32_e32 v0, v151
	v_min_u32_e32 v0, 32, v0
	v_lshlrev_b64 v[88:89], v0, v[150:151]
	v_min_u32_e32 v88, 1, v88
	v_or_b32_e32 v88, v89, v88
	v_cvt_f32_u32_e32 v88, v88
	v_sub_u32_e32 v0, 32, v0
	v_ldexp_f32 v0, v88, v0
	v_mul_f32_e32 v0, 0x33800000, v0
	v_fmamk_f32 v0, v0, 0x3b2aaaab, v226
	v_cvt_pk_bf16_f32 v96, v90, v91
	v_cvt_pk_bf16_f32 v97, v98, v99
	v_cvt_pk_bf16_f32 v98, v86, v87
	v_lshl_add_u64 v[86:87], v[118:119], 1, v[94:95]
	v_cvt_pk_bf16_f32 v99, v92, v93
	global_store_dwordx4 v[86:87], v[96:99], off offset:256 nt
	v_or_b32_e32 v86, 48, v140
	v_ashrrev_i32_e32 v87, 31, v86
	v_rsq_f32_e32 v88, v0
	s_nop 0
	v_mul_f32_e32 v88, s69, v88
	v_lshlrev_b64 v[92:93], 7, v[86:87]
	v_pk_mul_f32 v[90:91], v[84:85], v[88:89] op_sel_hi:[1,0]
	v_pk_mul_f32 v[82:83], v[82:83], v[88:89] op_sel_hi:[1,0]
	v_pk_mul_f32 v[84:85], v[80:81], v[88:89] op_sel_hi:[1,0]
	v_pk_mul_f32 v[78:79], v[78:79], v[88:89] op_sel_hi:[1,0]
	s_and_b64 vcc, exec, s[8:9]
	v_lshl_add_u64 v[80:81], s[20:21], 0, v[92:93]
	s_cbranch_vccnz .LBB0_727
	v_mov_b32_e32 v127, v1
	v_lshl_add_u64 v[96:97], v[80:81], 0, v[126:127]
	s_waitcnt vmcnt(14) lgkmcnt(0)
	v_mov_b64_e32 v[92:93], v[202:203]
	v_mov_b64_e32 v[94:95], v[204:205]
	v_mov_b64_e32 v[96:97], v[206:207]
	v_mov_b64_e32 v[98:99], v[208:209]
	v_pk_mul_f32 v[102:103], v[82:83], v[92:93] op_sel:[1,1] op_sel_hi:[0,1]
	v_mul_f32_e32 v0, v91, v95
	v_pk_mul_f32 v[100:101], v[82:83], v[92:93]
	v_pk_fma_f32 v[82:83], v[82:83], v[92:93], v[102:103] op_sel_hi:[1,0,1]
	v_pk_fma_f32 v[92:93], v[90:91], v[94:95], v[0:1] op_sel_hi:[1,1,0] neg_lo:[0,0,1] neg_hi:[0,0,1]
	v_mul_f32_e32 v0, v90, v95
	v_pk_fma_f32 v[94:95], v[90:91], v[94:95], v[0:1] op_sel:[1,0,0] op_sel_hi:[0,1,0]
	v_pk_mul_f32 v[104:105], v[78:79], v[96:97] op_sel:[1,1] op_sel_hi:[0,1]
	v_mul_f32_e32 v0, v85, v99
	v_pk_mul_f32 v[90:91], v[78:79], v[96:97]
	v_pk_fma_f32 v[78:79], v[78:79], v[96:97], v[104:105] op_sel_hi:[1,0,1]
	v_pk_fma_f32 v[96:97], v[84:85], v[98:99], v[0:1] op_sel_hi:[1,1,0] neg_lo:[0,0,1] neg_hi:[0,0,1]
	v_mul_f32_e32 v0, v84, v99
	v_pk_fma_f32 v[98:99], v[84:85], v[98:99], v[0:1] op_sel:[1,0,0] op_sel_hi:[0,1,0]
	v_sub_f32_e32 v82, v100, v102
	v_sub_f32_e32 v78, v90, v104
	v_mov_b32_e32 v90, v92
	v_mov_b32_e32 v91, v94
	v_mov_b32_e32 v84, v96
	v_mov_b32_e32 v85, v98
.LBB0_727:
	v_cvt_pk_bf16_f32 v92, v82, v83
	v_cvt_pk_bf16_f32 v93, v90, v91
	v_cvt_pk_bf16_f32 v94, v78, v79
	v_mov_b64_e32 v[78:79], s[16:17]
	v_mad_i64_i32 v[78:79], s[2:3], v86, s75, v[78:79]
	v_mov_b32_e32 v89, v88
	v_cvt_pk_bf16_f32 v95, v84, v85
	v_lshl_add_u64 v[82:83], v[128:129], 1, v[78:79]
	v_mov_b32_e32 v84, v88
	v_mov_b32_e32 v85, v88
	global_store_dwordx4 v[82:83], v[92:95], off nt
	v_pk_mul_f32 v[82:83], v[76:77], v[84:85]
	v_pk_mul_f32 v[74:75], v[74:75], v[88:89]
	v_pk_mul_f32 v[72:73], v[72:73], v[84:85]
	s_and_b64 vcc, exec, s[10:11]
	v_pk_mul_f32 v[70:71], v[70:71], v[88:89]
	s_cbranch_vccnz .LBB0_729
	v_mov_b32_e32 v127, v1
	v_lshl_add_u64 v[76:77], v[80:81], 0, v[126:127]
	s_waitcnt vmcnt(15) lgkmcnt(0)
	v_mov_b64_e32 v[84:85], v[202:203]
	v_mov_b64_e32 v[86:87], v[204:205]
	v_mov_b64_e32 v[88:89], v[206:207]
	v_mov_b64_e32 v[90:91], v[208:209]
	v_pk_mul_f32 v[80:81], v[74:75], v[84:85] op_sel:[1,1] op_sel_hi:[0,1]
	v_mul_f32_e32 v0, v83, v87
	v_pk_mul_f32 v[76:77], v[74:75], v[84:85]
	v_pk_fma_f32 v[74:75], v[74:75], v[84:85], v[80:81] op_sel_hi:[1,0,1]
	v_pk_fma_f32 v[84:85], v[82:83], v[86:87], v[0:1] op_sel_hi:[1,1,0] neg_lo:[0,0,1] neg_hi:[0,0,1]
	v_mul_f32_e32 v0, v82, v87
	v_pk_fma_f32 v[86:87], v[82:83], v[86:87], v[0:1] op_sel:[1,0,0] op_sel_hi:[0,1,0]
	v_pk_mul_f32 v[92:93], v[70:71], v[88:89] op_sel:[1,1] op_sel_hi:[0,1]
	v_mul_f32_e32 v0, v73, v91
	v_pk_mul_f32 v[82:83], v[70:71], v[88:89]
	v_pk_fma_f32 v[70:71], v[70:71], v[88:89], v[92:93] op_sel_hi:[1,0,1]
	v_pk_fma_f32 v[88:89], v[72:73], v[90:91], v[0:1] op_sel_hi:[1,1,0] neg_lo:[0,0,1] neg_hi:[0,0,1]
	v_mul_f32_e32 v0, v72, v91
	v_pk_fma_f32 v[90:91], v[72:73], v[90:91], v[0:1] op_sel:[1,0,0] op_sel_hi:[0,1,0]
	v_sub_f32_e32 v74, v76, v80
	v_sub_f32_e32 v70, v82, v92
	v_mov_b32_e32 v82, v84
	v_mov_b32_e32 v83, v86
	v_mov_b32_e32 v72, v88
	v_mov_b32_e32 v73, v90
.LBB0_729:
	v_ffbh_u32_e32 v0, v149
	v_min_u32_e32 v0, 32, v0
	v_lshlrev_b64 v[76:77], v0, v[148:149]
	v_min_u32_e32 v76, 1, v76
	v_or_b32_e32 v76, v77, v76
	v_cvt_f32_u32_e32 v76, v76
	v_sub_u32_e32 v0, 32, v0
	v_ldexp_f32 v0, v76, v0
	v_mul_f32_e32 v0, 0x33800000, v0
	v_fmamk_f32 v0, v0, 0x3b2aaaab, v226
	v_add_u32_e32 v80, 0x80, v140
	v_ashrrev_i32_e32 v81, 31, v80
	v_rsq_f32_e32 v76, v0
	s_nop 0
	v_mul_f32_e32 v76, s69, v76
	v_cvt_pk_bf16_f32 v84, v74, v75
	v_cvt_pk_bf16_f32 v85, v82, v83
	v_cvt_pk_bf16_f32 v86, v70, v71
	v_cvt_pk_bf16_f32 v87, v72, v73
	v_lshl_add_u64 v[70:71], v[118:119], 1, v[78:79]
	v_lshlrev_b64 v[72:73], 7, v[80:81]
	global_store_dwordx4 v[70:71], v[84:87], off offset:256 nt
	v_pk_mul_f32 v[70:71], v[68:69], v[76:77] op_sel_hi:[1,0]
	v_pk_mul_f32 v[66:67], v[66:67], v[76:77] op_sel_hi:[1,0]
	v_pk_mul_f32 v[68:69], v[64:65], v[76:77] op_sel_hi:[1,0]
	v_pk_mul_f32 v[62:63], v[62:63], v[76:77] op_sel_hi:[1,0]
	s_and_b64 vcc, exec, s[8:9]
	v_lshl_add_u64 v[64:65], s[20:21], 0, v[72:73]
	s_cbranch_vccnz .LBB0_731
	v_mov_b32_e32 v127, v1
	v_lshl_add_u64 v[78:79], v[64:65], 0, v[126:127]
	s_waitcnt vmcnt(14) lgkmcnt(0)
	v_mov_b64_e32 v[72:73], v[210:211]
	v_mov_b64_e32 v[74:75], v[212:213]
	v_mov_b64_e32 v[82:83], v[214:215]
	v_mov_b64_e32 v[84:85], v[216:217]
	v_pk_mul_f32 v[86:87], v[66:67], v[72:73] op_sel:[1,1] op_sel_hi:[0,1]
	v_mul_f32_e32 v0, v71, v75
	v_pk_mul_f32 v[78:79], v[66:67], v[72:73]
	v_pk_fma_f32 v[66:67], v[66:67], v[72:73], v[86:87] op_sel_hi:[1,0,1]
	v_pk_fma_f32 v[72:73], v[70:71], v[74:75], v[0:1] op_sel_hi:[1,1,0] neg_lo:[0,0,1] neg_hi:[0,0,1]
	v_mul_f32_e32 v0, v70, v75
	v_pk_fma_f32 v[74:75], v[70:71], v[74:75], v[0:1] op_sel:[1,0,0] op_sel_hi:[0,1,0]
	v_pk_mul_f32 v[88:89], v[62:63], v[82:83] op_sel:[1,1] op_sel_hi:[0,1]
	v_mul_f32_e32 v0, v69, v85
	v_pk_mul_f32 v[70:71], v[62:63], v[82:83]
	v_pk_fma_f32 v[62:63], v[62:63], v[82:83], v[88:89] op_sel_hi:[1,0,1]
	v_pk_fma_f32 v[82:83], v[68:69], v[84:85], v[0:1] op_sel_hi:[1,1,0] neg_lo:[0,0,1] neg_hi:[0,0,1]
	v_mul_f32_e32 v0, v68, v85
	v_pk_fma_f32 v[84:85], v[68:69], v[84:85], v[0:1] op_sel:[1,0,0] op_sel_hi:[0,1,0]
	v_sub_f32_e32 v66, v78, v86
	v_sub_f32_e32 v62, v70, v88
	v_mov_b32_e32 v70, v72
	v_mov_b32_e32 v71, v74
	v_mov_b32_e32 v68, v82
	v_mov_b32_e32 v69, v84
; __device__ __forceinline__ unsigned cvt_pk_bf16(float lo, float hi) { unsigned r; asm volatile("v_cvt_pk_bf16_f32 %0, %1, %2" : "=v"(r) : "v"(lo), "v"(hi)); return r; }
;     __device__ __forceinline__ void operator()(const f32x4 (&acc)[2][2][4][2], const Unit& u, int wr, int wc, int fr, int fq) const {
;     ...
;             for (int m = 0; m < 4; ++m) {
;                 const int row = row0 + ai * HALF + m * 16;
;                 const float rs = rsv[ai * 4 + m];
; #pragma unroll
;                 for (int bj = 0; bj < 2; ++bj) {
;                     const int colw = u.pn * BM + bj * HALF + wc * 32, col0 = colw + 8 * fq;
;                     const bool rope = (colw % 96) == 64 && colw < 576;
;                     f32x4 v0 = acc[ai][bj][m][0] * rs, v1 = acc[ai][bj][m][1] * rs;
;                     if (rope) {
;                         const float* tp = ropB + ((size_t)row * 16 + ((col0 - colw) >> 1)) * 2;
;                         const f32x4 c0 = *(const f32x4*)tp, c1 = *(const f32x4*)(tp + 4);
;                         f32x4 w0, w1;
;                         w0[0] = v0[0] * c0[0] - v0[1] * c0[1]; w0[1] = v0[1] * c0[0] + v0[0] * c0[1];
;                         w0[2] = v0[2] * c0[2] - v0[3] * c0[3]; w0[3] = v0[3] * c0[2] + v0[2] * c0[3];
;                         w1[0] = v1[0] * c1[0] - v1[1] * c1[1]; w1[1] = v1[1] * c1[0] + v1[0] * c1[1];
;                         w1[2] = v1[2] * c1[2] - v1[3] * c1[3]; w1[3] = v1[3] * c1[2] + v1[2] * c1[3];
;                         v0 = w0; v1 = w1;
;                     }
;                     u32x4 w; w.x = cvt_pk_bf16(v0[0], v0[1]); w.y = cvt_pk_bf16(v0[2], v0[3]); w.z = cvt_pk_bf16(v1[0], v1[1]); w.w = cvt_pk_bf16(v1[2], v1[3]);
;                     *(u32x4*)(O + (size_t)row * QMP + col0) = w;
.LBB0_731:
	v_cvt_pk_bf16_f32 v72, v66, v67
	v_cvt_pk_bf16_f32 v73, v70, v71
	v_cvt_pk_bf16_f32 v74, v62, v63
	v_mov_b64_e32 v[62:63], s[16:17]
	v_mad_i64_i32 v[62:63], s[2:3], v80, s75, v[62:63]
	v_mov_b32_e32 v77, v76
	v_cvt_pk_bf16_f32 v75, v68, v69
	v_lshl_add_u64 v[66:67], v[128:129], 1, v[62:63]
	v_mov_b32_e32 v68, v76
	v_mov_b32_e32 v69, v76
	global_store_dwordx4 v[66:67], v[72:75], off nt
	v_pk_mul_f32 v[66:67], v[60:61], v[68:69]
	v_pk_mul_f32 v[58:59], v[58:59], v[76:77]
	v_pk_mul_f32 v[60:61], v[56:57], v[68:69]
	s_and_b64 vcc, exec, s[10:11]
	v_pk_mul_f32 v[54:55], v[54:55], v[76:77]
	s_cbranch_vccnz .LBB0_733
	v_mov_b32_e32 v127, v1
	v_lshl_add_u64 v[56:57], v[64:65], 0, v[126:127]
	s_waitcnt vmcnt(15) lgkmcnt(0)
	v_mov_b64_e32 v[68:69], v[210:211]
	v_mov_b64_e32 v[70:71], v[212:213]
	v_mov_b64_e32 v[72:73], v[214:215]
	v_mov_b64_e32 v[74:75], v[216:217]
	v_pk_mul_f32 v[64:65], v[58:59], v[68:69] op_sel:[1,1] op_sel_hi:[0,1]
	v_mul_f32_e32 v0, v67, v71
	v_pk_mul_f32 v[56:57], v[58:59], v[68:69]
	v_pk_fma_f32 v[58:59], v[58:59], v[68:69], v[64:65] op_sel_hi:[1,0,1]
	v_pk_fma_f32 v[68:69], v[66:67], v[70:71], v[0:1] op_sel_hi:[1,1,0] neg_lo:[0,0,1] neg_hi:[0,0,1]
	v_mul_f32_e32 v0, v66, v71
	v_pk_fma_f32 v[70:71], v[66:67], v[70:71], v[0:1] op_sel:[1,0,0] op_sel_hi:[0,1,0]
	v_pk_mul_f32 v[76:77], v[54:55], v[72:73] op_sel:[1,1] op_sel_hi:[0,1]
	v_mul_f32_e32 v0, v61, v75
	v_pk_mul_f32 v[66:67], v[54:55], v[72:73]
	v_pk_fma_f32 v[54:55], v[54:55], v[72:73], v[76:77] op_sel_hi:[1,0,1]
	v_pk_fma_f32 v[72:73], v[60:61], v[74:75], v[0:1] op_sel_hi:[1,1,0] neg_lo:[0,0,1] neg_hi:[0,0,1]
	v_mul_f32_e32 v0, v60, v75
	v_pk_fma_f32 v[74:75], v[60:61], v[74:75], v[0:1] op_sel:[1,0,0] op_sel_hi:[0,1,0]
	v_sub_f32_e32 v58, v56, v64
	v_sub_f32_e32 v54, v66, v76
	v_mov_b32_e32 v66, v68
	v_mov_b32_e32 v67, v70
	v_mov_b32_e32 v60, v72
	v_mov_b32_e32 v61, v74
.LBB0_733:
	v_ffbh_u32_e32 v0, v147
	v_min_u32_e32 v0, 32, v0
	v_lshlrev_b64 v[56:57], v0, v[146:147]
	v_min_u32_e32 v56, 1, v56
	v_or_b32_e32 v56, v57, v56
	v_cvt_f32_u32_e32 v56, v56
	v_sub_u32_e32 v0, 32, v0
	v_ldexp_f32 v0, v56, v0
	v_mul_f32_e32 v0, 0x33800000, v0
	v_fmamk_f32 v0, v0, 0x3b2aaaab, v226
	v_cvt_pk_bf16_f32 v64, v58, v59
	v_cvt_pk_bf16_f32 v65, v66, v67
	v_cvt_pk_bf16_f32 v66, v54, v55
	v_lshl_add_u64 v[54:55], v[118:119], 1, v[62:63]
	v_cvt_pk_bf16_f32 v67, v60, v61
	global_store_dwordx4 v[54:55], v[64:67], off offset:256 nt
	v_add_u32_e32 v54, 0x90, v140
	v_ashrrev_i32_e32 v55, 31, v54
	v_rsq_f32_e32 v56, v0
	s_nop 0
	v_mul_f32_e32 v56, s69, v56
	v_lshlrev_b64 v[60:61], 7, v[54:55]
	v_pk_mul_f32 v[58:59], v[52:53], v[56:57] op_sel_hi:[1,0]
	v_pk_mul_f32 v[50:51], v[50:51], v[56:57] op_sel_hi:[1,0]
	v_pk_mul_f32 v[52:53], v[48:49], v[56:57] op_sel_hi:[1,0]
	v_pk_mul_f32 v[46:47], v[46:47], v[56:57] op_sel_hi:[1,0]
	s_and_b64 vcc, exec, s[8:9]
	v_lshl_add_u64 v[48:49], s[20:21], 0, v[60:61]
	s_cbranch_vccnz .LBB0_735
	v_mov_b32_e32 v127, v1
	v_lshl_add_u64 v[64:65], v[48:49], 0, v[126:127]
	s_waitcnt vmcnt(14) lgkmcnt(0)
	v_mov_b64_e32 v[60:61], v[218:219]
	v_mov_b64_e32 v[62:63], v[220:221]
	v_mov_b64_e32 v[64:65], v[228:229]
	v_mov_b64_e32 v[66:67], v[230:231]
	v_pk_mul_f32 v[70:71], v[50:51], v[60:61] op_sel:[1,1] op_sel_hi:[0,1]
	v_mul_f32_e32 v0, v59, v63
	v_pk_mul_f32 v[68:69], v[50:51], v[60:61]
	v_pk_fma_f32 v[50:51], v[50:51], v[60:61], v[70:71] op_sel_hi:[1,0,1]
	v_pk_fma_f32 v[60:61], v[58:59], v[62:63], v[0:1] op_sel_hi:[1,1,0] neg_lo:[0,0,1] neg_hi:[0,0,1]
	v_mul_f32_e32 v0, v58, v63
	v_pk_fma_f32 v[62:63], v[58:59], v[62:63], v[0:1] op_sel:[1,0,0] op_sel_hi:[0,1,0]
	v_pk_mul_f32 v[72:73], v[46:47], v[64:65] op_sel:[1,1] op_sel_hi:[0,1]
	v_mul_f32_e32 v0, v53, v67
	v_pk_mul_f32 v[58:59], v[46:47], v[64:65]
	v_pk_fma_f32 v[46:47], v[46:47], v[64:65], v[72:73] op_sel_hi:[1,0,1]
	v_pk_fma_f32 v[64:65], v[52:53], v[66:67], v[0:1] op_sel_hi:[1,1,0] neg_lo:[0,0,1] neg_hi:[0,0,1]
	v_mul_f32_e32 v0, v52, v67
	v_pk_fma_f32 v[66:67], v[52:53], v[66:67], v[0:1] op_sel:[1,0,0] op_sel_hi:[0,1,0]
	v_sub_f32_e32 v50, v68, v70
	v_sub_f32_e32 v46, v58, v72
	v_mov_b32_e32 v58, v60
	v_mov_b32_e32 v59, v62
	v_mov_b32_e32 v52, v64
	v_mov_b32_e32 v53, v66
.LBB0_735:
	v_cvt_pk_bf16_f32 v60, v50, v51
	v_cvt_pk_bf16_f32 v61, v58, v59
	v_cvt_pk_bf16_f32 v62, v46, v47
	v_mov_b64_e32 v[46:47], s[16:17]
	v_mad_i64_i32 v[46:47], s[2:3], v54, s75, v[46:47]
	v_mov_b32_e32 v57, v56
	v_cvt_pk_bf16_f32 v63, v52, v53
	v_lshl_add_u64 v[50:51], v[128:129], 1, v[46:47]
	v_mov_b32_e32 v52, v56
	v_mov_b32_e32 v53, v56
	global_store_dwordx4 v[50:51], v[60:63], off nt
	v_pk_mul_f32 v[50:51], v[44:45], v[52:53]
	v_pk_mul_f32 v[42:43], v[42:43], v[56:57]
	v_pk_mul_f32 v[44:45], v[40:41], v[52:53]
	s_and_b64 vcc, exec, s[10:11]
	v_pk_mul_f32 v[38:39], v[38:39], v[56:57]
	s_cbranch_vccnz .LBB0_737
	v_mov_b32_e32 v127, v1
	v_lshl_add_u64 v[40:41], v[48:49], 0, v[126:127]
	s_waitcnt vmcnt(15) lgkmcnt(0)
	v_mov_b64_e32 v[52:53], v[218:219]
	v_mov_b64_e32 v[54:55], v[220:221]
	v_mov_b64_e32 v[56:57], v[228:229]
	v_mov_b64_e32 v[58:59], v[230:231]
	v_pk_mul_f32 v[48:49], v[42:43], v[52:53] op_sel:[1,1] op_sel_hi:[0,1]
	v_mul_f32_e32 v0, v51, v55
	v_pk_mul_f32 v[40:41], v[42:43], v[52:53]
	v_pk_fma_f32 v[42:43], v[42:43], v[52:53], v[48:49] op_sel_hi:[1,0,1]
	v_pk_fma_f32 v[52:53], v[50:51], v[54:55], v[0:1] op_sel_hi:[1,1,0] neg_lo:[0,0,1] neg_hi:[0,0,1]
	v_mul_f32_e32 v0, v50, v55
	v_pk_fma_f32 v[54:55], v[50:51], v[54:55], v[0:1] op_sel:[1,0,0] op_sel_hi:[0,1,0]
	v_pk_mul_f32 v[60:61], v[38:39], v[56:57] op_sel:[1,1] op_sel_hi:[0,1]
	v_mul_f32_e32 v0, v45, v59
	v_pk_mul_f32 v[50:51], v[38:39], v[56:57]
	v_pk_fma_f32 v[38:39], v[38:39], v[56:57], v[60:61] op_sel_hi:[1,0,1]
	v_pk_fma_f32 v[56:57], v[44:45], v[58:59], v[0:1] op_sel_hi:[1,1,0] neg_lo:[0,0,1] neg_hi:[0,0,1]
	v_mul_f32_e32 v0, v44, v59
	v_pk_fma_f32 v[58:59], v[44:45], v[58:59], v[0:1] op_sel:[1,0,0] op_sel_hi:[0,1,0]
	v_sub_f32_e32 v42, v40, v48
	v_sub_f32_e32 v38, v50, v60
	v_mov_b32_e32 v50, v52
	v_mov_b32_e32 v51, v54
	v_mov_b32_e32 v44, v56
	v_mov_b32_e32 v45, v58
; __device__ __forceinline__ unsigned cvt_pk_bf16(float lo, float hi) { unsigned r; asm volatile("v_cvt_pk_bf16_f32 %0, %1, %2" : "=v"(r) : "v"(lo), "v"(hi)); return r; }
;     __device__ __forceinline__ void operator()(const f32x4 (&acc)[2][2][4][2], const Unit& u, int wr, int wc, int fr, int fq) const {
;     ...
;             for (int m = 0; m < 4; ++m) {
;                 const int row = row0 + ai * HALF + m * 16;
;                 const float rs = rsv[ai * 4 + m];
; #pragma unroll
;                 for (int bj = 0; bj < 2; ++bj) {
;                     const int colw = u.pn * BM + bj * HALF + wc * 32, col0 = colw + 8 * fq;
;                     const bool rope = (colw % 96) == 64 && colw < 576;
;                     f32x4 v0 = acc[ai][bj][m][0] * rs, v1 = acc[ai][bj][m][1] * rs;
;                     if (rope) {
;                         const float* tp = ropB + ((size_t)row * 16 + ((col0 - colw) >> 1)) * 2;
;                         const f32x4 c0 = *(const f32x4*)tp, c1 = *(const f32x4*)(tp + 4);
;                         f32x4 w0, w1;
;                         w0[0] = v0[0] * c0[0] - v0[1] * c0[1]; w0[1] = v0[1] * c0[0] + v0[0] * c0[1];
;                         w0[2] = v0[2] * c0[2] - v0[3] * c0[3]; w0[3] = v0[3] * c0[2] + v0[2] * c0[3];
;                         w1[0] = v1[0] * c1[0] - v1[1] * c1[1]; w1[1] = v1[1] * c1[0] + v1[0] * c1[1];
;                         w1[2] = v1[2] * c1[2] - v1[3] * c1[3]; w1[3] = v1[3] * c1[2] + v1[2] * c1[3];
;                         v0 = w0; v1 = w1;
;                     }
;                     u32x4 w; w.x = cvt_pk_bf16(v0[0], v0[1]); w.y = cvt_pk_bf16(v0[2], v0[3]); w.z = cvt_pk_bf16(v1[0], v1[1]); w.w = cvt_pk_bf16(v1[2], v1[3]);
;                     *(u32x4*)(O + (size_t)row * QMP + col0) = w;
.LBB0_737:
	v_ffbh_u32_e32 v0, v145
	v_min_u32_e32 v0, 32, v0
	v_lshlrev_b64 v[40:41], v0, v[144:145]
	v_min_u32_e32 v40, 1, v40
	v_or_b32_e32 v40, v41, v40
	v_cvt_f32_u32_e32 v40, v40
	v_sub_u32_e32 v0, 32, v0
	v_ldexp_f32 v0, v40, v0
	v_mul_f32_e32 v0, 0x33800000, v0
	v_fmamk_f32 v0, v0, 0x3b2aaaab, v226
	v_cvt_pk_bf16_f32 v48, v42, v43
	v_cvt_pk_bf16_f32 v49, v50, v51
	v_cvt_pk_bf16_f32 v50, v38, v39
	v_lshl_add_u64 v[38:39], v[118:119], 1, v[46:47]
	v_cvt_pk_bf16_f32 v51, v44, v45
	global_store_dwordx4 v[38:39], v[48:51], off offset:256 nt
	v_add_u32_e32 v38, 0xa0, v140
	v_ashrrev_i32_e32 v39, 31, v38
	v_rsq_f32_e32 v40, v0
	s_nop 0
	v_mul_f32_e32 v40, s69, v40
	v_lshlrev_b64 v[44:45], 7, v[38:39]
	v_pk_mul_f32 v[42:43], v[36:37], v[40:41] op_sel_hi:[1,0]
	v_pk_mul_f32 v[34:35], v[34:35], v[40:41] op_sel_hi:[1,0]
	v_pk_mul_f32 v[36:37], v[32:33], v[40:41] op_sel_hi:[1,0]
	v_pk_mul_f32 v[30:31], v[30:31], v[40:41] op_sel_hi:[1,0]
	s_and_b64 vcc, exec, s[8:9]
	v_lshl_add_u64 v[32:33], s[20:21], 0, v[44:45]
	s_cbranch_vccnz .LBB0_739
	v_mov_b32_e32 v127, v1
	v_lshl_add_u64 v[48:49], v[32:33], 0, v[126:127]
	s_waitcnt vmcnt(14) lgkmcnt(0)
	v_mov_b64_e32 v[44:45], v[232:233]
	v_mov_b64_e32 v[46:47], v[234:235]
	v_mov_b64_e32 v[48:49], v[236:237]
	v_mov_b64_e32 v[50:51], v[238:239]
	v_pk_mul_f32 v[54:55], v[34:35], v[44:45] op_sel:[1,1] op_sel_hi:[0,1]
	v_mul_f32_e32 v0, v43, v47
	v_pk_mul_f32 v[52:53], v[34:35], v[44:45]
	v_pk_fma_f32 v[34:35], v[34:35], v[44:45], v[54:55] op_sel_hi:[1,0,1]
	v_pk_fma_f32 v[44:45], v[42:43], v[46:47], v[0:1] op_sel_hi:[1,1,0] neg_lo:[0,0,1] neg_hi:[0,0,1]
	v_mul_f32_e32 v0, v42, v47
	v_pk_fma_f32 v[46:47], v[42:43], v[46:47], v[0:1] op_sel:[1,0,0] op_sel_hi:[0,1,0]
	v_pk_mul_f32 v[56:57], v[30:31], v[48:49] op_sel:[1,1] op_sel_hi:[0,1]
	v_mul_f32_e32 v0, v37, v51
	v_pk_mul_f32 v[42:43], v[30:31], v[48:49]
	v_pk_fma_f32 v[30:31], v[30:31], v[48:49], v[56:57] op_sel_hi:[1,0,1]
	v_pk_fma_f32 v[48:49], v[36:37], v[50:51], v[0:1] op_sel_hi:[1,1,0] neg_lo:[0,0,1] neg_hi:[0,0,1]
	v_mul_f32_e32 v0, v36, v51
	v_pk_fma_f32 v[50:51], v[36:37], v[50:51], v[0:1] op_sel:[1,0,0] op_sel_hi:[0,1,0]
	v_sub_f32_e32 v34, v52, v54
	v_sub_f32_e32 v30, v42, v56
	v_mov_b32_e32 v42, v44
	v_mov_b32_e32 v43, v46
	v_mov_b32_e32 v36, v48
	v_mov_b32_e32 v37, v50
.LBB0_739:
	v_cvt_pk_bf16_f32 v44, v34, v35
	v_cvt_pk_bf16_f32 v45, v42, v43
	v_cvt_pk_bf16_f32 v46, v30, v31
	v_mov_b64_e32 v[30:31], s[16:17]
	v_mad_i64_i32 v[30:31], s[2:3], v38, s75, v[30:31]
	v_mov_b32_e32 v41, v40
	v_cvt_pk_bf16_f32 v47, v36, v37
	v_lshl_add_u64 v[34:35], v[128:129], 1, v[30:31]
	v_mov_b32_e32 v36, v40
	v_mov_b32_e32 v37, v40
	global_store_dwordx4 v[34:35], v[44:47], off nt
	v_pk_mul_f32 v[34:35], v[28:29], v[36:37]
	v_pk_mul_f32 v[26:27], v[26:27], v[40:41]
	v_pk_mul_f32 v[28:29], v[24:25], v[36:37]
	s_and_b64 vcc, exec, s[10:11]
	v_pk_mul_f32 v[22:23], v[22:23], v[40:41]
	s_cbranch_vccnz .LBB0_741
	v_mov_b32_e32 v127, v1
	v_lshl_add_u64 v[24:25], v[32:33], 0, v[126:127]
	s_waitcnt vmcnt(15) lgkmcnt(0)
	v_mov_b64_e32 v[36:37], v[232:233]
	v_mov_b64_e32 v[38:39], v[234:235]
	v_mov_b64_e32 v[40:41], v[236:237]
	v_mov_b64_e32 v[42:43], v[238:239]
	v_pk_mul_f32 v[32:33], v[26:27], v[36:37] op_sel:[1,1] op_sel_hi:[0,1]
	v_mul_f32_e32 v0, v35, v39
	v_pk_mul_f32 v[24:25], v[26:27], v[36:37]
	v_pk_fma_f32 v[26:27], v[26:27], v[36:37], v[32:33] op_sel_hi:[1,0,1]
	v_pk_fma_f32 v[36:37], v[34:35], v[38:39], v[0:1] op_sel_hi:[1,1,0] neg_lo:[0,0,1] neg_hi:[0,0,1]
	v_mul_f32_e32 v0, v34, v39
	v_pk_fma_f32 v[38:39], v[34:35], v[38:39], v[0:1] op_sel:[1,0,0] op_sel_hi:[0,1,0]
	v_pk_mul_f32 v[44:45], v[22:23], v[40:41] op_sel:[1,1] op_sel_hi:[0,1]
	v_mul_f32_e32 v0, v29, v43
	v_pk_mul_f32 v[34:35], v[22:23], v[40:41]
	v_pk_fma_f32 v[22:23], v[22:23], v[40:41], v[44:45] op_sel_hi:[1,0,1]
	v_pk_fma_f32 v[40:41], v[28:29], v[42:43], v[0:1] op_sel_hi:[1,1,0] neg_lo:[0,0,1] neg_hi:[0,0,1]
	v_mul_f32_e32 v0, v28, v43
	v_pk_fma_f32 v[42:43], v[28:29], v[42:43], v[0:1] op_sel:[1,0,0] op_sel_hi:[0,1,0]
	v_sub_f32_e32 v26, v24, v32
	v_sub_f32_e32 v22, v34, v44
	v_mov_b32_e32 v34, v36
	v_mov_b32_e32 v35, v38
	v_mov_b32_e32 v28, v40
	v_mov_b32_e32 v29, v42
; __device__ __forceinline__ unsigned cvt_pk_bf16(float lo, float hi) { unsigned r; asm volatile("v_cvt_pk_bf16_f32 %0, %1, %2" : "=v"(r) : "v"(lo), "v"(hi)); return r; }
;     __device__ __forceinline__ void operator()(const f32x4 (&acc)[2][2][4][2], const Unit& u, int wr, int wc, int fr, int fq) const {
;     ...
;             for (int m = 0; m < 4; ++m) {
;                 const int row = row0 + ai * HALF + m * 16;
;                 const float rs = rsv[ai * 4 + m];
; #pragma unroll
;                 for (int bj = 0; bj < 2; ++bj) {
;                     const int colw = u.pn * BM + bj * HALF + wc * 32, col0 = colw + 8 * fq;
;                     const bool rope = (colw % 96) == 64 && colw < 576;
;                     f32x4 v0 = acc[ai][bj][m][0] * rs, v1 = acc[ai][bj][m][1] * rs;
;                     if (rope) {
;                         const float* tp = ropB + ((size_t)row * 16 + ((col0 - colw) >> 1)) * 2;
;                         const f32x4 c0 = *(const f32x4*)tp, c1 = *(const f32x4*)(tp + 4);
;                         f32x4 w0, w1;
;                         w0[0] = v0[0] * c0[0] - v0[1] * c0[1]; w0[1] = v0[1] * c0[0] + v0[0] * c0[1];
;                         w0[2] = v0[2] * c0[2] - v0[3] * c0[3]; w0[3] = v0[3] * c0[2] + v0[2] * c0[3];
;                         w1[0] = v1[0] * c1[0] - v1[1] * c1[1]; w1[1] = v1[1] * c1[0] + v1[0] * c1[1];
;                         w1[2] = v1[2] * c1[2] - v1[3] * c1[3]; w1[3] = v1[3] * c1[2] + v1[2] * c1[3];
;                         v0 = w0; v1 = w1;
;                     }
;                     u32x4 w; w.x = cvt_pk_bf16(v0[0], v0[1]); w.y = cvt_pk_bf16(v0[2], v0[3]); w.z = cvt_pk_bf16(v1[0], v1[1]); w.w = cvt_pk_bf16(v1[2], v1[3]);
;                     *(u32x4*)(O + (size_t)row * QMP + col0) = w;
.LBB0_741:
	v_ffbh_u32_e32 v0, v143
	v_min_u32_e32 v0, 32, v0
	v_lshlrev_b64 v[24:25], v0, v[142:143]
	v_min_u32_e32 v24, 1, v24
	v_or_b32_e32 v24, v25, v24
	v_cvt_f32_u32_e32 v24, v24
	v_sub_u32_e32 v0, 32, v0
	v_ldexp_f32 v0, v24, v0
	v_mul_f32_e32 v0, 0x33800000, v0
	v_fmamk_f32 v0, v0, 0x3b2aaaab, v226
	v_cvt_pk_bf16_f32 v32, v26, v27
	v_cvt_pk_bf16_f32 v33, v34, v35
	v_cvt_pk_bf16_f32 v34, v22, v23
	v_lshl_add_u64 v[22:23], v[118:119], 1, v[30:31]
	v_cvt_pk_bf16_f32 v35, v28, v29
	global_store_dwordx4 v[22:23], v[32:35], off offset:256 nt
	v_add_u32_e32 v22, 0xb0, v140
	v_ashrrev_i32_e32 v23, 31, v22
	v_rsq_f32_e32 v24, v0
	s_nop 0
	v_mul_f32_e32 v24, s69, v24
	v_lshlrev_b64 v[28:29], 7, v[22:23]
	v_pk_mul_f32 v[26:27], v[20:21], v[24:25] op_sel_hi:[1,0]
	v_pk_mul_f32 v[18:19], v[18:19], v[24:25] op_sel_hi:[1,0]
	v_pk_mul_f32 v[20:21], v[12:13], v[24:25] op_sel_hi:[1,0]
	v_pk_mul_f32 v[12:13], v[10:11], v[24:25] op_sel_hi:[1,0]
	s_and_b64 vcc, exec, s[8:9]
	v_lshl_add_u64 v[10:11], s[20:21], 0, v[28:29]
	s_cbranch_vccnz .LBB0_743
	v_mov_b32_e32 v127, v1
	v_lshl_add_u64 v[32:33], v[10:11], 0, v[126:127]
	s_waitcnt vmcnt(14) lgkmcnt(0)
	v_mov_b64_e32 v[28:29], v[240:241]
	v_mov_b64_e32 v[30:31], v[242:243]
	v_mov_b64_e32 v[32:33], v[244:245]
	v_mov_b64_e32 v[34:35], v[246:247]
	v_pk_mul_f32 v[38:39], v[18:19], v[28:29] op_sel:[1,1] op_sel_hi:[0,1]
	v_mul_f32_e32 v0, v27, v31
	v_pk_mul_f32 v[36:37], v[18:19], v[28:29]
	v_pk_fma_f32 v[18:19], v[18:19], v[28:29], v[38:39] op_sel_hi:[1,0,1]
	v_pk_fma_f32 v[28:29], v[26:27], v[30:31], v[0:1] op_sel_hi:[1,1,0] neg_lo:[0,0,1] neg_hi:[0,0,1]
	v_mul_f32_e32 v0, v26, v31
	v_pk_fma_f32 v[30:31], v[26:27], v[30:31], v[0:1] op_sel:[1,0,0] op_sel_hi:[0,1,0]
	v_pk_mul_f32 v[40:41], v[12:13], v[32:33] op_sel:[1,1] op_sel_hi:[0,1]
	v_mul_f32_e32 v0, v21, v35
	v_pk_mul_f32 v[26:27], v[12:13], v[32:33]
	v_pk_fma_f32 v[12:13], v[12:13], v[32:33], v[40:41] op_sel_hi:[1,0,1]
	v_pk_fma_f32 v[32:33], v[20:21], v[34:35], v[0:1] op_sel_hi:[1,1,0] neg_lo:[0,0,1] neg_hi:[0,0,1]
	v_mul_f32_e32 v0, v20, v35
	v_pk_fma_f32 v[34:35], v[20:21], v[34:35], v[0:1] op_sel:[1,0,0] op_sel_hi:[0,1,0]
	v_sub_f32_e32 v18, v36, v38
	v_sub_f32_e32 v12, v26, v40
	v_mov_b32_e32 v26, v28
	v_mov_b32_e32 v27, v30
	v_mov_b32_e32 v20, v32
	v_mov_b32_e32 v21, v34
.LBB0_743:
	v_cvt_pk_bf16_f32 v28, v18, v19
	v_cvt_pk_bf16_f32 v29, v26, v27
	v_cvt_pk_bf16_f32 v30, v12, v13
	v_mov_b64_e32 v[12:13], s[16:17]
	v_mad_i64_i32 v[12:13], s[2:3], v22, s75, v[12:13]
	v_lshl_add_u64 v[18:19], v[128:129], 1, v[12:13]
	v_mov_b32_e32 v25, v24
	v_cvt_pk_bf16_f32 v31, v20, v21
	global_store_dwordx4 v[18:19], v[28:31], off nt
	v_mov_b32_e32 v18, v24
	v_mov_b32_e32 v19, v24
	v_pk_mul_f32 v[8:9], v[8:9], v[18:19]
	v_pk_mul_f32 v[6:7], v[6:7], v[24:25]
	v_pk_mul_f32 v[4:5], v[4:5], v[18:19]
	s_and_b64 vcc, exec, s[10:11]
	v_pk_mul_f32 v[2:3], v[2:3], v[24:25]
	s_cbranch_vccnz .LBB0_745
	v_mov_b32_e32 v127, v1
	v_lshl_add_u64 v[10:11], v[10:11], 0, v[126:127]
	s_waitcnt vmcnt(15) lgkmcnt(0)
	v_mov_b64_e32 v[18:19], v[240:241]
	v_mov_b64_e32 v[20:21], v[242:243]
	v_mov_b64_e32 v[22:23], v[244:245]
	v_mov_b64_e32 v[24:25], v[246:247]
	v_pk_mul_f32 v[26:27], v[6:7], v[18:19] op_sel:[1,1] op_sel_hi:[0,1]
	v_mul_f32_e32 v0, v9, v21
	v_pk_mul_f32 v[10:11], v[6:7], v[18:19]
	v_pk_fma_f32 v[6:7], v[6:7], v[18:19], v[26:27] op_sel_hi:[1,0,1]
	v_pk_fma_f32 v[18:19], v[8:9], v[20:21], v[0:1] op_sel_hi:[1,1,0] neg_lo:[0,0,1] neg_hi:[0,0,1]
	v_mul_f32_e32 v0, v8, v21
	v_pk_fma_f32 v[20:21], v[8:9], v[20:21], v[0:1] op_sel:[1,0,0] op_sel_hi:[0,1,0]
	v_pk_mul_f32 v[28:29], v[2:3], v[22:23] op_sel:[1,1] op_sel_hi:[0,1]
	v_mul_f32_e32 v0, v5, v25
	v_pk_mul_f32 v[8:9], v[2:3], v[22:23]
	v_pk_fma_f32 v[2:3], v[2:3], v[22:23], v[28:29] op_sel_hi:[1,0,1]
	v_pk_fma_f32 v[22:23], v[4:5], v[24:25], v[0:1] op_sel_hi:[1,1,0] neg_lo:[0,0,1] neg_hi:[0,0,1]
	v_mul_f32_e32 v0, v4, v25
	v_pk_fma_f32 v[24:25], v[4:5], v[24:25], v[0:1] op_sel:[1,0,0] op_sel_hi:[0,1,0]
	v_sub_f32_e32 v6, v10, v26
	v_sub_f32_e32 v2, v8, v28
	v_mov_b32_e32 v8, v18
	v_mov_b32_e32 v9, v20
	v_mov_b32_e32 v4, v22
	v_mov_b32_e32 v5, v24
